# CONV4: conv loop fully software-pipelined (rows two items ahead into alternating sets, next item's weights one ahead, single counted vmcnt(3) per item); replaces CONV3
# baseline (speedup 1.0000x reference)
; __device__ __forceinline__ void conv_fetch(const bf16_t* raw, int item, int tid, u32x4 (&rg)[3]) {
;     constexpr int NFB = 80;
;     const int ch = item / NFB, fb = item % NFB;
;     const bool is_ctx = ch < (CGR / 128);
;     const long row0 = (long)ch * 128;
; #pragma unroll
;     for (int i = 0; i < 3; ++i) {
;         const int idx = tid + 512 * i;
;         rg[i] = (u32x4){0u, 0u, 0u, 0u};
;         if (idx < 134 * 8) { const int ir = idx >> 3, c8 = idx & 7; int tok; bool ok;
;             if (is_ctx) { tok = ir - 2; const int gt = (ch & 1) * 128 + tok; ok = (ir < 131) && gt >= 0 && gt < 256; }
;             else { const int sg = ir >= 67 ? 1 : 0, q = ir - 67 * sg; tok = 64 * sg + q - 2; ok = q >= 2 && q < 66; }
;             if (ok) rg[i] = *(const u32x4*)(raw + (size_t)(row0 + tok) * NA + fb * 64 + c8 * 8); }
;     }
; __device__ __forceinline__ void phase_conv(const Params& p, LAS unsigned char* lds, int wg, int G, int tid) {
;     ...
;     u32x4 rg[3];
;     int item = wg, buf = 0;
;     if (item < NIT) conv_fetch(raw, item, tid, rg);
.LBB0_625:
	s_andn2_b64 vcc, exec, s[4:5]
	s_cbranch_vccnz .LBB0_674
	v_lshlrev_b32_e32 v12, 3, v240
	v_and_b32_e32 v50, 56, v12
	v_lshlrev_b32_e32 v192, 1, v50
	v_lshl_add_u64 v[20:21], s[0:1], 0, v[192:193]
	s_movk_i32 s0, 0x430
	v_cmp_gt_i32_e64 s[2:3], s0, v240
	v_ashrrev_i32_e32 v13, 3, v240
	s_movk_i32 s0, 0x42
	v_cmp_lt_i32_e32 vcc, s0, v13
	v_mov_b32_e32 v17, 0xffffffbd
	v_add_u32_e32 v51, -2, v13
	v_cndmask_b32_e32 v14, 0, v17, vcc
	s_movk_i32 s1, 0x83
	v_cndmask_b32_e64 v15, 0, 64, vcc
	v_add_u32_e32 v14, v14, v51
	v_cmp_gt_i32_e64 s[6:7], s1, v13
	v_add_u32_e32 v13, 0x200, v240
	v_add_u32_e32 v52, v14, v15
	v_cmp_gt_u32_e64 s[4:5], 64, v14
	v_ashrrev_i32_e32 v14, 3, v13
	v_cmp_lt_i32_e32 vcc, s0, v14
	v_add_u32_e32 v53, -2, v14
	v_cmp_gt_i32_e64 s[12:13], s1, v14
	v_cndmask_b32_e32 v15, 0, v17, vcc
	v_cndmask_b32_e64 v16, 0, 64, vcc
	v_add_u32_e32 v15, v15, v53
	v_add_u32_e32 v14, 0x400, v240
	v_add_u32_e32 v54, v15, v16
	v_cmp_gt_u32_e64 s[10:11], 64, v15
	v_ashrrev_i32_e32 v15, 3, v14
	v_cmp_lt_i32_e32 vcc, s0, v15
	v_add_u32_e32 v55, -2, v15
	v_cmp_gt_i32_e64 s[18:19], s1, v15
	v_cndmask_b32_e32 v16, 0, v17, vcc
	v_cndmask_b32_e64 v17, 0, 64, vcc
	v_add_u32_e32 v16, v16, v55
	v_add_u32_e32 v56, v16, v17
	v_cmp_gt_u32_e64 s[16:17], 64, v16
	v_ashrrev_i32_e32 v16, 2, v240
	v_lshrrev_b32_e32 v15, 8, v240
	v_and_b32_e32 v22, -8, v16
	v_and_b32_e32 v16, 56, v16
	s_movk_i32 s0, 0x43
	v_readlane_b32 s20, v255, 31
	v_mad_u32_u24 v59, v15, s0, v16
	v_readlane_b32 s21, v255, 32
	s_add_u32 s0, s20, 0x1000
	s_addc_u32 s1, s21, 0
	s_add_u32 s24, s20, 0x2000
	s_addc_u32 s25, s21, 0
	s_mov_b32 s93, s88
	s_mov_b32 s88, s26
	s_mov_b64 s[96:97], s[38:39]
	s_add_u32 s26, s20, 0x3000
	v_readlane_b32 s36, v255, 19
	s_addc_u32 s27, s21, 0
	v_readlane_b32 s38, v255, 21
	v_readlane_b32 s39, v255, 22
	s_add_u32 s28, s38, 0x4000
	s_addc_u32 s29, s39, 0
	s_add_u32 s30, s38, 0x8000
	v_and_b32_e32 v60, 0xffffffc0, v12
	v_lshlrev_b32_e32 v12, 3, v13
	s_addc_u32 s31, s39, 0
	s_movk_i32 s8, 0x230
	v_and_b32_e32 v57, 31, v245
	v_ashrrev_i32_e32 v23, 31, v22
	v_and_b32_e32 v61, 0xffffffc0, v12
	v_lshlrev_b32_e32 v12, 3, v14
	v_readlane_b32 s37, v255, 20
	v_readlane_b32 s41, v255, 24
	s_add_u32 s36, s38, 0xc000
	s_mov_b64 s[72:73], s[84:85]
	s_mov_b64 s[68:69], s[86:87]
	s_mov_b32 s54, s76
	s_mov_b64 s[76:77], s[60:61]
	s_mov_b64 s[60:61], s[44:45]
	s_mov_b32 s33, 0
	v_cmp_gt_i32_e64 s[8:9], s8, v240
	v_cmp_gt_i32_e64 s[14:15], 48, v240
	v_lshlrev_b32_e32 v58, 1, v57
	v_and_b32_e32 v62, 0xffffffc0, v12
	s_addc_u32 s37, s39, 0
	v_lshlrev_b64 v[24:25], 11, v[22:23]
	s_lshl_b32 s38, s92, 6
	s_lshl_b32 s39, s34, 6
	s_mov_b32 s41, s92
	v_readlane_b32 s22, v255, 33
	v_readlane_b32 s23, v255, 34
	v_readlane_b32 s40, v255, 23
	v_readlane_b32 s42, v255, 25
	v_readlane_b32 s43, v255, 26
	s_add_i32 s40, s41, s34
	s_mul_hi_i32 s20, s40, 0x66666667
	s_lshr_b32 s21, s20, 31
	s_ashr_i32 s20, s20, 5
	s_add_i32 s20, s20, s21
	s_cmpk_lt_i32 s40, 0xa00
	s_cselect_b64 vcc, -1, 0
	s_ashr_i32 s21, s20, 31
	s_lshl_b64 s[22:23], s[20:21], 7
	s_lshl_b32 s21, s20, 7
	s_and_b32 s45, s21, 0x80
	s_mulk_i32 s20, 0xec00
	s_add_i32 s21, s39, s38
	s_add_i32 s20, s21, s20
	s_ashr_i32 s21, s20, 31
	v_lshl_add_u64 v[66:67], s[20:21], 1, v[20:21]
	v_mov_b32_e32 v104, 0
	v_mov_b32_e32 v100, 0
	v_mov_b32_e32 v101, 0
	v_mov_b32_e32 v102, 0
	v_mov_b32_e32 v103, 0
	s_and_saveexec_b64 s[48:49], s[2:3]
	v_add_u32_e32 v100, s45, v51
	s_movk_i32 s20, 0x100
	v_cmp_gt_u32_e64 s[20:21], s20, v100
	s_and_b64 s[20:21], s[6:7], s[20:21]
	v_cndmask_b32_e64 v101, 0, 1, s[4:5]
	v_cndmask_b32_e64 v100, 0, 1, s[20:21]
	v_cndmask_b32_e32 v100, v101, v100, vcc
	v_and_b32_e32 v100, 1, v100
	v_cmp_eq_u32_e64 s[20:21], 1, v100
	v_mov_b32_e32 v103, 0
	v_mov_b32_e32 v102, 0
	v_mov_b32_e32 v101, 0
	v_mov_b32_e32 v100, 0
	s_and_saveexec_b64 s[50:51], s[20:21]
	v_cndmask_b32_e32 v100, v52, v51, vcc
	v_ashrrev_i32_e32 v101, 31, v100
	v_lshl_add_u64 v[100:101], s[22:23], 0, v[100:101]
	v_mad_u64_u32 v[102:103], s[20:21], v100, s78, v[66:67]
	v_mad_i32_i24 v103, v101, s78, v103
	global_load_dwordx4 v[100:103], v[102:103], off

; __device__ __forceinline__ void conv_fetch(const bf16_t* raw, int item, int tid, u32x4 (&rg)[3]) {
;     ...
;     for (int i = 0; i < 3; ++i) {
;         const int idx = tid + 512 * i;
;         rg[i] = (u32x4){0u, 0u, 0u, 0u};
;         if (idx < 134 * 8) { const int ir = idx >> 3, c8 = idx & 7; int tok; bool ok;
;             if (is_ctx) { tok = ir - 2; const int gt = (ch & 1) * 128 + tok; ok = (ir < 131) && gt >= 0 && gt < 256; }
;             else { const int sg = ir >= 67 ? 1 : 0, q = ir - 67 * sg; tok = 64 * sg + q - 2; ok = q >= 2 && q < 66; }
;             if (ok) rg[i] = *(const u32x4*)(raw + (size_t)(row0 + tok) * NA + fb * 64 + c8 * 8); }
;     }
.Lconv_pb_637:
	s_or_b64 exec, exec, s[48:49]
	v_mov_b32_e32 v105, 0
	v_mov_b32_e32 v106, 0
	v_mov_b32_e32 v107, 0
	s_and_saveexec_b64 s[48:49], s[8:9]
	v_add_u32_e32 v104, s45, v53
	s_movk_i32 s20, 0x100
	v_cmp_gt_u32_e64 s[20:21], s20, v104
	s_and_b64 s[20:21], s[12:13], s[20:21]
	v_cndmask_b32_e64 v105, 0, 1, s[10:11]
	v_cndmask_b32_e64 v104, 0, 1, s[20:21]
	v_cndmask_b32_e32 v104, v105, v104, vcc
	v_and_b32_e32 v104, 1, v104
	v_cmp_eq_u32_e64 s[20:21], 1, v104
	v_mov_b32_e32 v107, 0
	v_mov_b32_e32 v106, 0
	v_mov_b32_e32 v105, 0
	v_mov_b32_e32 v104, 0
	s_and_saveexec_b64 s[50:51], s[20:21]
	v_cndmask_b32_e32 v104, v54, v53, vcc
	v_ashrrev_i32_e32 v105, 31, v104
	v_lshl_add_u64 v[104:105], s[22:23], 0, v[104:105]
	v_mad_u64_u32 v[106:107], s[20:21], v104, s78, v[66:67]
	v_mad_i32_i24 v107, v105, s78, v107
	global_load_dwordx4 v[104:107], v[106:107], off

; __device__ __forceinline__ void conv_fetch(const bf16_t* raw, int item, int tid, u32x4 (&rg)[3]) {
;     ...
;     for (int i = 0; i < 3; ++i) {
;         const int idx = tid + 512 * i;
;         rg[i] = (u32x4){0u, 0u, 0u, 0u};
;         if (idx < 134 * 8) { const int ir = idx >> 3, c8 = idx & 7; int tok; bool ok;
;             if (is_ctx) { tok = ir - 2; const int gt = (ch & 1) * 128 + tok; ok = (ir < 131) && gt >= 0 && gt < 256; }
;             else { const int sg = ir >= 67 ? 1 : 0, q = ir - 67 * sg; tok = 64 * sg + q - 2; ok = q >= 2 && q < 66; }
;             if (ok) rg[i] = *(const u32x4*)(raw + (size_t)(row0 + tok) * NA + fb * 64 + c8 * 8); }
;     }
.Lconv_pb_641:
	s_or_b64 exec, exec, s[48:49]
	v_mov_b32_e32 v111, 0
	v_mov_b32_e32 v110, 0
	v_mov_b32_e32 v109, 0
	v_mov_b32_e32 v108, 0
	s_and_saveexec_b64 s[48:49], s[14:15]
	v_add_u32_e32 v108, s45, v55
	s_movk_i32 s20, 0x100
	v_cmp_gt_u32_e64 s[20:21], s20, v108
	s_and_b64 s[20:21], s[18:19], s[20:21]
	v_cndmask_b32_e64 v109, 0, 1, s[16:17]
	v_cndmask_b32_e64 v108, 0, 1, s[20:21]
	v_cndmask_b32_e32 v108, v109, v108, vcc
	v_and_b32_e32 v108, 1, v108
	v_cmp_eq_u32_e64 s[20:21], 1, v108
	v_mov_b32_e32 v111, 0
	v_mov_b32_e32 v110, 0
	v_mov_b32_e32 v109, 0
	v_mov_b32_e32 v108, 0
	s_and_saveexec_b64 s[50:51], s[20:21]
	v_cndmask_b32_e32 v108, v56, v55, vcc
	v_ashrrev_i32_e32 v109, 31, v108
	v_lshl_add_u64 v[108:109], s[22:23], 0, v[108:109]
	v_mad_u64_u32 v[110:111], s[20:21], v108, s78, v[66:67]
	v_mad_i32_i24 v111, v109, s78, v111
	global_load_dwordx4 v[108:111], v[110:111], off

; __device__ __forceinline__ void phase_conv(const Params& p, LAS unsigned char* lds, int wg, int G, int tid) {
;     ...
;         const int ch = item / NFB, fb = item % NFB;
;         const size_t row0 = (size_t)ch * 128;
;         const int fp = tid & 31, tq = tid >> 5;
;         const int feat = fb * 64 + 2 * fp;
;         f32x2 w0, w1, w2, w3, bias;
;         if (feat < 4096) { w0 = *(const f32x2*)(p.ssd_conv_w + feat); w1 = *(const f32x2*)(p.ssd_conv_w + 4096 + feat); w2 = *(const f32x2*)(p.ssd_conv_w + 8192 + feat); w3 = *(const f32x2*)(p.ssd_conv_w + 12288 + feat); bias = *(const f32x2*)(p.ssd_conv_b + feat); }
;         else { const int lf = feat - 4096; w0 = *(const f32x2*)(p.lru_conv_w + lf); w1 = *(const f32x2*)(p.lru_conv_w + 1024 + lf); w2 = *(const f32x2*)(p.lru_conv_w + 2048 + lf); w3 = *(const f32x2*)(p.lru_conv_w + 3072 + lf); bias = *(const f32x2*)(p.lru_conv_b + lf); }
.Lconv_pb_645:
	s_or_b64 exec, exec, s[48:49]
	s_mul_hi_i32 s20, s41, 0x66666667
	s_lshr_b32 s21, s20, 31
	s_ashr_i32 s20, s20, 5
	s_add_i32 s100, s20, s21
	s_mul_i32 s20, s100, 0xffffec00
	s_add_i32 s20, s20, s38
	v_add_u32_e32 v90, s20, v58
	s_movk_i32 s20, 0xfff
	v_cmp_lt_i32_e32 vcc, s20, v90
	s_and_saveexec_b64 s[20:21], vcc
	s_xor_b64 s[20:21], exec, s[20:21]
	s_cbranch_execz .Lconv_pw_648
	v_add_u32_e32 v192, 0xfffff000, v90
	v_readlane_b32 s80, v255, 31
	v_lshlrev_b64 v[94:95], 2, v[192:193]
	v_readlane_b32 s81, v255, 32
	v_readlane_b32 s82, v255, 33
	v_readlane_b32 s83, v255, 34
	v_lshl_add_u64 v[96:97], s[80:81], 0, v[94:95]
	v_lshl_add_u64 v[98:99], s[0:1], 0, v[94:95]
	v_lshl_add_u64 v[112:113], s[24:25], 0, v[94:95]
	v_lshl_add_u64 v[114:115], s[26:27], 0, v[94:95]
	v_lshl_add_u64 v[94:95], s[82:83], 0, v[94:95]
.Lconv_pw_648:
	s_andn2_saveexec_b64 s[20:21], s[20:21]
	s_cbranch_execz .Lconv_pw_650
	v_ashrrev_i32_e32 v91, 31, v90
	v_readlane_b32 s80, v255, 19
	v_lshlrev_b64 v[94:95], 2, v[90:91]
	v_readlane_b32 s82, v255, 21
	v_readlane_b32 s83, v255, 22
	v_readlane_b32 s84, v255, 23
	v_readlane_b32 s85, v255, 24
	v_lshl_add_u64 v[96:97], s[82:83], 0, v[94:95]
	v_lshl_add_u64 v[98:99], s[28:29], 0, v[94:95]
	v_lshl_add_u64 v[112:113], s[30:31], 0, v[94:95]
	v_lshl_add_u64 v[114:115], s[36:37], 0, v[94:95]
	v_lshl_add_u64 v[94:95], s[84:85], 0, v[94:95]
	v_readlane_b32 s81, v255, 20
	v_readlane_b32 s86, v255, 25
	v_readlane_b32 s87, v255, 26
.Lconv_pw_650:
	s_or_b64 exec, exec, s[20:21]
	global_load_dwordx2 v[80:81], v[96:97], off
	global_load_dwordx2 v[82:83], v[94:95], off
	global_load_dwordx2 v[88:89], v[98:99], off
	global_load_dwordx2 v[86:87], v[112:113], off
	global_load_dwordx2 v[84:85], v[114:115], off
	s_waitcnt vmcnt(0)
	s_branch .LBB0_628

; #define LAS __attribute__((address_space(3)))
; __device__ __forceinline__ void phase_conv(const Params& p, LAS unsigned char* lds, int wg, int G, int tid) {
;     ...
;         const int ch = item / NFB, fb = item % NFB;
;         const size_t row0 = (size_t)ch * 128;
;         const int fp = tid & 31, tq = tid >> 5;
;         const int feat = fb * 64 + 2 * fp;
;         f32x2 w0, w1, w2, w3, bias;
;         if (feat < 4096) { w0 = *(const f32x2*)(p.ssd_conv_w + feat); w1 = *(const f32x2*)(p.ssd_conv_w + 4096 + feat); w2 = *(const f32x2*)(p.ssd_conv_w + 8192 + feat); w3 = *(const f32x2*)(p.ssd_conv_w + 12288 + feat); bias = *(const f32x2*)(p.ssd_conv_b + feat); }
;         else { const int lf = feat - 4096; w0 = *(const f32x2*)(p.lru_conv_w + lf); w1 = *(const f32x2*)(p.lru_conv_w + 1024 + lf); w2 = *(const f32x2*)(p.lru_conv_w + 2048 + lf); w3 = *(const f32x2*)(p.lru_conv_w + 3072 + lf); bias = *(const f32x2*)(p.lru_conv_b + lf); }
;         const bool is_ctx = ch < (CGR / 128);
;         const bool act = fb < 64;
;         f32x2 o[8];
;         const int ib0 = is_ctx ? tq * 8 : (tq >> 3) * 67 + (tq & 7) * 8;
;         const LAS f32x2* tp = (const LAS f32x2*)tile + fp;
;         f32x2 v0 = tp[(ib0 + 0) * 32], v1 = tp[(ib0 + 1) * 32], v2 = tp[(ib0 + 2) * 32];
; #pragma unroll
;         for (int k = 0; k < 8; ++k) {
;             const f32x2 v3 = tp[(ib0 + k + 3) * 32];
;             f32x2 a = bias + w0 * v0 + w1 * v1 + w2 * v2 + w3 * v3;
.LBB0_646:
	s_mul_hi_i32 s20, s41, 0x66666667
	s_lshr_b32 s21, s20, 31
	s_ashr_i32 s20, s20, 5
	s_add_i32 s48, s20, s21
	s_mul_i32 s20, s48, 0xffffec00
	s_add_i32 s20, s20, s38
	v_add_u32_e32 v26, s20, v58
	v_mov_b32_e32 v30, v80
	v_mov_b32_e32 v31, v81
	v_mov_b32_e32 v32, v82
	v_mov_b32_e32 v33, v83
	v_mov_b32_e32 v34, v84
	v_mov_b32_e32 v35, v85
	v_mov_b32_e32 v36, v86
	v_mov_b32_e32 v37, v87
	v_mov_b32_e32 v38, v88
	v_mov_b32_e32 v39, v89
	s_mul_i32 s20, s48, 0xffffffb0
	s_add_i32 s45, s41, s20
	s_cmpk_lt_i32 s41, 0xa00
	s_cselect_b64 s[20:21], -1, 0
	v_cndmask_b32_e64 v12, v59, v22, s[20:21]
	v_lshl_add_u32 v13, v57, 3, s44
	v_lshlrev_b32_e32 v12, 8, v12
	v_add_u32_e32 v27, v13, v12
	ds_read2_b64 v[16:19], v27 offset1:32
	ds_read2_b64 v[12:15], v27 offset0:64 offset1:96
	s_cmp_lt_i32 s45, 64
	s_cselect_b64 s[50:51], -1, 0
	s_cmp_gt_i32 s45, 63
	s_waitcnt lgkmcnt(1)
	v_pk_fma_f32 v[16:17], v[30:31], v[16:17], v[32:33]
	v_pk_fma_f32 v[16:17], v[38:39], v[18:19], v[16:17]
	s_waitcnt lgkmcnt(0)
	v_pk_fma_f32 v[16:17], v[36:37], v[12:13], v[16:17]
	v_pk_fma_f32 v[16:17], v[34:35], v[14:15], v[16:17]
	s_mov_b32 s101, s45
	v_writelane_b32 v255, s48, 63
	v_writelane_b32 v255, s50, 59
	v_writelane_b32 v255, s51, 60
	v_writelane_b32 v255, s20, 61
	v_writelane_b32 v255, s21, 62
	s_and_b64 vcc, exec, s[42:43]
	s_cbranch_vccnz .Lconv_nopf
	s_mul_hi_i32 s20, s40, 0x66666667
	s_lshr_b32 s21, s20, 31
	s_ashr_i32 s20, s20, 5
	s_add_i32 s100, s20, s21
	s_mul_i32 s20, s100, 0xffffec00
	s_add_i32 s20, s20, s38
	s_add_i32 s20, s20, s39
	v_add_u32_e32 v90, s20, v58
	s_movk_i32 s20, 0xfff
	v_cmp_lt_i32_e32 vcc, s20, v90
	s_and_saveexec_b64 s[20:21], vcc
	s_xor_b64 s[20:21], exec, s[20:21]
	s_cbranch_execz .Lconv_lw_648
	v_add_u32_e32 v192, 0xfffff000, v90
	v_readlane_b32 s80, v255, 31
	v_lshlrev_b64 v[94:95], 2, v[192:193]
	v_readlane_b32 s81, v255, 32
	v_readlane_b32 s82, v255, 33
	v_readlane_b32 s83, v255, 34
	v_lshl_add_u64 v[96:97], s[80:81], 0, v[94:95]
	v_lshl_add_u64 v[98:99], s[0:1], 0, v[94:95]
	v_lshl_add_u64 v[112:113], s[24:25], 0, v[94:95]
	v_lshl_add_u64 v[114:115], s[26:27], 0, v[94:95]
	v_lshl_add_u64 v[94:95], s[82:83], 0, v[94:95]

; __device__ __forceinline__ void conv_fetch(const bf16_t* raw, int item, int tid, u32x4 (&rg)[3]) {
;     ...
;     for (int i = 0; i < 3; ++i) {
;         const int idx = tid + 512 * i;
;         rg[i] = (u32x4){0u, 0u, 0u, 0u};
;         if (idx < 134 * 8) { const int ir = idx >> 3, c8 = idx & 7; int tok; bool ok;
;             if (is_ctx) { tok = ir - 2; const int gt = (ch & 1) * 128 + tok; ok = (ir < 131) && gt >= 0 && gt < 256; }
;             else { const int sg = ir >= 67 ? 1 : 0, q = ir - 67 * sg; tok = 64 * sg + q - 2; ok = q >= 2 && q < 66; }
;             if (ok) rg[i] = *(const u32x4*)(raw + (size_t)(row0 + tok) * NA + fb * 64 + c8 * 8); }
; __device__ __forceinline__ void phase_conv(const Params& p, LAS unsigned char* lds, int wg, int G, int tid) {
;     ...
;         if (item + G < NIT) conv_fetch(raw, item + G, tid, rg);
;         const int ch = item / NFB, fb = item % NFB;
;         const size_t row0 = (size_t)ch * 128;
;         const int fp = tid & 31, tq = tid >> 5;
;         const int feat = fb * 64 + 2 * fp;
;         f32x2 w0, w1, w2, w3, bias;
;         if (feat < 4096) { w0 = *(const f32x2*)(p.ssd_conv_w + feat); w1 = *(const f32x2*)(p.ssd_conv_w + 4096 + feat); w2 = *(const f32x2*)(p.ssd_conv_w + 8192 + feat); w3 = *(const f32x2*)(p.ssd_conv_w + 12288 + feat); bias = *(const f32x2*)(p.ssd_conv_b + feat); }
;         else { const int lf = feat - 4096; w0 = *(const f32x2*)(p.lru_conv_w + lf); w1 = *(const f32x2*)(p.lru_conv_w + 1024 + lf); w2 = *(const f32x2*)(p.lru_conv_w + 2048 + lf); w3 = *(const f32x2*)(p.lru_conv_w + 3072 + lf); bias = *(const f32x2*)(p.lru_conv_b + lf); }
.Lconv_lw_650:
	s_or_b64 exec, exec, s[20:21]
	global_load_dwordx2 v[80:81], v[96:97], off
	global_load_dwordx2 v[82:83], v[94:95], off
	global_load_dwordx2 v[88:89], v[98:99], off
	global_load_dwordx2 v[86:87], v[112:113], off
	global_load_dwordx2 v[84:85], v[114:115], off
	s_add_i32 s100, s40, s34
	s_cmpk_gt_i32 s100, 0x59ff
	s_cbranch_scc1 .Lconv_nopf
	s_cmp_eq_u32 s33, 0
	s_cbranch_scc0 .Lconv_toB
	s_mul_hi_i32 s20, s100, 0x66666667
	s_lshr_b32 s21, s20, 31
	s_ashr_i32 s20, s20, 5
	s_add_i32 s20, s20, s21
	s_cmpk_lt_i32 s100, 0xa00
	s_cselect_b64 vcc, -1, 0
	s_ashr_i32 s21, s20, 31
	s_lshl_b64 s[22:23], s[20:21], 7
	s_lshl_b32 s21, s20, 7
	s_and_b32 s45, s21, 0x80
	s_mulk_i32 s20, 0xec00
	s_add_i32 s21, s39, s38
	s_add_i32 s21, s21, s39
	s_add_i32 s20, s21, s20
	s_ashr_i32 s21, s20, 31
	v_lshl_add_u64 v[66:67], s[20:21], 1, v[20:21]
	v_mov_b32_e32 v72, 0
	v_mov_b32_e32 v68, 0
	v_mov_b32_e32 v69, 0
	v_mov_b32_e32 v70, 0
	v_mov_b32_e32 v71, 0
	s_and_saveexec_b64 s[48:49], s[2:3]
	v_add_u32_e32 v68, s45, v51
	s_movk_i32 s20, 0x100
	v_cmp_gt_u32_e64 s[20:21], s20, v68
	s_and_b64 s[20:21], s[6:7], s[20:21]
	v_cndmask_b32_e64 v69, 0, 1, s[4:5]
	v_cndmask_b32_e64 v68, 0, 1, s[20:21]
	v_cndmask_b32_e32 v68, v69, v68, vcc
	v_and_b32_e32 v68, 1, v68
	v_cmp_eq_u32_e64 s[20:21], 1, v68
	v_mov_b32_e32 v71, 0
	v_mov_b32_e32 v70, 0
	v_mov_b32_e32 v69, 0
	v_mov_b32_e32 v68, 0
	s_and_saveexec_b64 s[50:51], s[20:21]
	v_cndmask_b32_e32 v68, v52, v51, vcc
	v_ashrrev_i32_e32 v69, 31, v68
	v_lshl_add_u64 v[68:69], s[22:23], 0, v[68:69]
	v_mad_u64_u32 v[70:71], s[20:21], v68, s78, v[66:67]
	v_mad_i32_i24 v71, v69, s78, v71
	global_load_dwordx4 v[68:71], v[70:71], off

; __device__ __forceinline__ void conv_fetch(const bf16_t* raw, int item, int tid, u32x4 (&rg)[3]) {
;     ...
;     for (int i = 0; i < 3; ++i) {
;         const int idx = tid + 512 * i;
;         rg[i] = (u32x4){0u, 0u, 0u, 0u};
;         if (idx < 134 * 8) { const int ir = idx >> 3, c8 = idx & 7; int tok; bool ok;
;             if (is_ctx) { tok = ir - 2; const int gt = (ch & 1) * 128 + tok; ok = (ir < 131) && gt >= 0 && gt < 256; }
;             else { const int sg = ir >= 67 ? 1 : 0, q = ir - 67 * sg; tok = 64 * sg + q - 2; ok = q >= 2 && q < 66; }
;             if (ok) rg[i] = *(const u32x4*)(raw + (size_t)(row0 + tok) * NA + fb * 64 + c8 * 8); }
;     }
.Lconv_la_637:
	s_or_b64 exec, exec, s[48:49]
	v_mov_b32_e32 v73, 0
	v_mov_b32_e32 v74, 0
	v_mov_b32_e32 v75, 0
	s_and_saveexec_b64 s[48:49], s[8:9]
	v_add_u32_e32 v72, s45, v53
	s_movk_i32 s20, 0x100
	v_cmp_gt_u32_e64 s[20:21], s20, v72
	s_and_b64 s[20:21], s[12:13], s[20:21]
	v_cndmask_b32_e64 v73, 0, 1, s[10:11]
	v_cndmask_b32_e64 v72, 0, 1, s[20:21]
	v_cndmask_b32_e32 v72, v73, v72, vcc
	v_and_b32_e32 v72, 1, v72
	v_cmp_eq_u32_e64 s[20:21], 1, v72
	v_mov_b32_e32 v75, 0
	v_mov_b32_e32 v74, 0
	v_mov_b32_e32 v73, 0
	v_mov_b32_e32 v72, 0
	s_and_saveexec_b64 s[50:51], s[20:21]
	v_cndmask_b32_e32 v72, v54, v53, vcc
	v_ashrrev_i32_e32 v73, 31, v72
	v_lshl_add_u64 v[72:73], s[22:23], 0, v[72:73]
	v_mad_u64_u32 v[74:75], s[20:21], v72, s78, v[66:67]
	v_mad_i32_i24 v75, v73, s78, v75
	global_load_dwordx4 v[72:75], v[74:75], off

; __device__ __forceinline__ void conv_fetch(const bf16_t* raw, int item, int tid, u32x4 (&rg)[3]) {
;     ...
;     for (int i = 0; i < 3; ++i) {
;         const int idx = tid + 512 * i;
;         rg[i] = (u32x4){0u, 0u, 0u, 0u};
;         if (idx < 134 * 8) { const int ir = idx >> 3, c8 = idx & 7; int tok; bool ok;
;             if (is_ctx) { tok = ir - 2; const int gt = (ch & 1) * 128 + tok; ok = (ir < 131) && gt >= 0 && gt < 256; }
;             else { const int sg = ir >= 67 ? 1 : 0, q = ir - 67 * sg; tok = 64 * sg + q - 2; ok = q >= 2 && q < 66; }
;             if (ok) rg[i] = *(const u32x4*)(raw + (size_t)(row0 + tok) * NA + fb * 64 + c8 * 8); }
;     }
.Lconv_la_641:
	s_or_b64 exec, exec, s[48:49]
	v_mov_b32_e32 v79, 0
	v_mov_b32_e32 v78, 0
	v_mov_b32_e32 v77, 0
	v_mov_b32_e32 v76, 0
	s_and_saveexec_b64 s[48:49], s[14:15]
	v_add_u32_e32 v76, s45, v55
	s_movk_i32 s20, 0x100
	v_cmp_gt_u32_e64 s[20:21], s20, v76
	s_and_b64 s[20:21], s[18:19], s[20:21]
	v_cndmask_b32_e64 v77, 0, 1, s[16:17]
	v_cndmask_b32_e64 v76, 0, 1, s[20:21]
	v_cndmask_b32_e32 v76, v77, v76, vcc
	v_and_b32_e32 v76, 1, v76
	v_cmp_eq_u32_e64 s[20:21], 1, v76
	v_mov_b32_e32 v79, 0
	v_mov_b32_e32 v78, 0
	v_mov_b32_e32 v77, 0
	v_mov_b32_e32 v76, 0
	s_and_saveexec_b64 s[50:51], s[20:21]
	v_cndmask_b32_e32 v76, v56, v55, vcc
	v_ashrrev_i32_e32 v77, 31, v76
	v_lshl_add_u64 v[76:77], s[22:23], 0, v[76:77]
	v_mad_u64_u32 v[78:79], s[20:21], v76, s78, v[66:67]
	v_mad_i32_i24 v79, v77, s78, v79
	global_load_dwordx4 v[76:79], v[78:79], off

; __device__ __forceinline__ void conv_fetch(const bf16_t* raw, int item, int tid, u32x4 (&rg)[3]) {
;     ...
;     for (int i = 0; i < 3; ++i) {
;         const int idx = tid + 512 * i;
;         rg[i] = (u32x4){0u, 0u, 0u, 0u};
;         if (idx < 134 * 8) { const int ir = idx >> 3, c8 = idx & 7; int tok; bool ok;
;             if (is_ctx) { tok = ir - 2; const int gt = (ch & 1) * 128 + tok; ok = (ir < 131) && gt >= 0 && gt < 256; }
;             else { const int sg = ir >= 67 ? 1 : 0, q = ir - 67 * sg; tok = 64 * sg + q - 2; ok = q >= 2 && q < 66; }
;             if (ok) rg[i] = *(const u32x4*)(raw + (size_t)(row0 + tok) * NA + fb * 64 + c8 * 8); }
.Lconv_la_645:
	s_or_b64 exec, exec, s[48:49]
	s_branch .Lconv_nopf
.Lconv_toB:
	s_mul_hi_i32 s20, s100, 0x66666667
	s_lshr_b32 s21, s20, 31
	s_ashr_i32 s20, s20, 5
	s_add_i32 s20, s20, s21
	s_cmpk_lt_i32 s100, 0xa00
	s_cselect_b64 vcc, -1, 0
	s_ashr_i32 s21, s20, 31
	s_lshl_b64 s[22:23], s[20:21], 7
	s_lshl_b32 s21, s20, 7
	s_and_b32 s45, s21, 0x80
	s_mulk_i32 s20, 0xec00
	s_add_i32 s21, s39, s38
	s_add_i32 s21, s21, s39
	s_add_i32 s20, s21, s20
	s_ashr_i32 s21, s20, 31
	v_lshl_add_u64 v[66:67], s[20:21], 1, v[20:21]
	v_mov_b32_e32 v104, 0
	v_mov_b32_e32 v100, 0
	v_mov_b32_e32 v101, 0
	v_mov_b32_e32 v102, 0
	v_mov_b32_e32 v103, 0
	s_and_saveexec_b64 s[48:49], s[2:3]
	v_add_u32_e32 v100, s45, v51
	s_movk_i32 s20, 0x100
	v_cmp_gt_u32_e64 s[20:21], s20, v100
	s_and_b64 s[20:21], s[6:7], s[20:21]
	v_cndmask_b32_e64 v101, 0, 1, s[4:5]
	v_cndmask_b32_e64 v100, 0, 1, s[20:21]
	v_cndmask_b32_e32 v100, v101, v100, vcc
	v_and_b32_e32 v100, 1, v100
	v_cmp_eq_u32_e64 s[20:21], 1, v100
	v_mov_b32_e32 v103, 0
	v_mov_b32_e32 v102, 0
	v_mov_b32_e32 v101, 0
	v_mov_b32_e32 v100, 0
	s_and_saveexec_b64 s[50:51], s[20:21]
	v_cndmask_b32_e32 v100, v52, v51, vcc
	v_ashrrev_i32_e32 v101, 31, v100
	v_lshl_add_u64 v[100:101], s[22:23], 0, v[100:101]
	v_mad_u64_u32 v[102:103], s[20:21], v100, s78, v[66:67]
	v_mad_i32_i24 v103, v101, s78, v103
	global_load_dwordx4 v[100:103], v[102:103], off

; #define LAS __attribute__((address_space(3)))
; __device__ __forceinline__ float bflo(unsigned w) { return __uint_as_float(w << 16); }
; __device__ __forceinline__ float bfhi(unsigned w) { return __uint_as_float(w & 0xffff0000u); }
; __device__ __forceinline__ void phase_conv(const Params& p, LAS unsigned char* lds, int wg, int G, int tid) {
;     ...
;     for (; item < NIT; item += G) {
;         LAS float* tile = (LAS float*)(lds + buf * 34816);
; #pragma unroll
;         for (int i = 0; i < 3; ++i) { const int idx = tid + 512 * i;
;             if (idx < 134 * 8) { LAS float* d = tile + (idx >> 3) * 64 + (idx & 7) * 8; const u32x4 w = rg[i];
;                 *(LAS f32x4*)d = (f32x4){bflo(w.x), bfhi(w.x), bflo(w.y), bfhi(w.y)}; *(LAS f32x4*)(d + 4) = (f32x4){bflo(w.z), bfhi(w.z), bflo(w.w), bfhi(w.w)}; } }
;         __syncthreads();
;         if (item + G < NIT) conv_fetch(raw, item + G, tid, rg);
.LBB0_666:
	s_add_i32 s100, s40, s34
	s_cmpk_gt_i32 s100, 0x59ff
	s_cbranch_scc1 .Lconv_w0
	s_waitcnt vmcnt(3)
	s_branch .Lconv_wd

; #define LAS __attribute__((address_space(3)))
; __device__ __forceinline__ float bflo(unsigned w) { return __uint_as_float(w << 16); }
; __device__ __forceinline__ float bfhi(unsigned w) { return __uint_as_float(w & 0xffff0000u); }
; __device__ __forceinline__ void phase_conv(const Params& p, LAS unsigned char* lds, int wg, int G, int tid) {
;     ...
;         LAS float* tile = (LAS float*)(lds + buf * 34816);
; #pragma unroll
;         for (int i = 0; i < 3; ++i) { const int idx = tid + 512 * i;
;             if (idx < 134 * 8) { LAS float* d = tile + (idx >> 3) * 64 + (idx & 7) * 8; const u32x4 w = rg[i];
;                 *(LAS f32x4*)d = (f32x4){bflo(w.x), bfhi(w.x), bflo(w.y), bfhi(w.y)}; *(LAS f32x4*)(d + 4) = (f32x4){bflo(w.z), bfhi(w.z), bflo(w.w), bfhi(w.w)}; } }
.Lconv_wd:
	s_cmp_eq_u32 s33, 0
	s_cbranch_scc1 .Lconv_cB
	v_mov_b32_e32 v0, v68
	v_mov_b32_e32 v1, v69
	v_mov_b32_e32 v2, v70
	v_mov_b32_e32 v3, v71
	v_mov_b32_e32 v4, v72
	v_mov_b32_e32 v5, v73
	v_mov_b32_e32 v6, v74
	v_mov_b32_e32 v7, v75
	v_mov_b32_e32 v8, v76
	v_mov_b32_e32 v9, v77
	v_mov_b32_e32 v10, v78
	v_mov_b32_e32 v11, v79
	s_branch .Lconv_cd
.Lconv_cB:
	v_mov_b32_e32 v0, v100
	v_mov_b32_e32 v1, v101
	v_mov_b32_e32 v2, v102
	v_mov_b32_e32 v3, v103
	v_mov_b32_e32 v4, v104
	v_mov_b32_e32 v5, v105
	v_mov_b32_e32 v6, v106
	v_mov_b32_e32 v7, v107
	v_mov_b32_e32 v8, v108
	v_mov_b32_e32 v9, v109
	v_mov_b32_e32 v10, v110
	v_mov_b32_e32 v11, v111
